# v24 + the seven accumulator-clearing MFMAs issued inside the scalar next-tile computation (spaced between SALU), own copy on the no-next-tile path
# baseline (speedup 1.0000x reference)
;     __device__ __forceinline__ bool next(int i, Unit& u) const {
;         const long L = (long)i * G + c; if (L >= nwg) return false;
;         int wgid = (int)L; { const int q = nwg / NXCD, r = nwg % NXCD, xcd = wgid % NXCD, off = wgid / NXCD; wgid = (xcd < r ? xcd * (q + 1) : r * (q + 1) + (xcd - r) * q) + off; }
;         const int nig = WGM * nN, gid = wgid / nig, fm = gid * WGM, gsz = (nM - fm) < WGM ? (nM - fm) : WGM;
;         u.pm = fm + ((wgid % nig) % gsz); u.pn = (wgid % nig) / gsz; return true;
;     }
; template <class Epi>
; __device__ __forceinline__ void gemm_phase(LAS unsigned char* lds, int wave_s, const Gemm g, const StaticOrder S, const Epi E) {
;     ...
; #pragma unroll
;         for (int a = 0; a < 2; ++a)
; #pragma unroll
;             for (int b = 0; b < 2; ++b)
; #pragma unroll
;                 for (int m = 0; m < 4; ++m)
; #pragma unroll
;                     for (int n = 0; n < 2; ++n) acc[a][b][m][n] = (f32x4){0.f, 0.f, 0.f, 0.f};
.LBB0_162:
	v_mov_b32_e32 v246, 0
	v_mov_b32_e32 v247, 0
	v_mov_b32_e32 v248, 0
	v_mov_b32_e32 v249, 0
	s_add_i32 s43, s43, 1
	v_readlane_b32 s0, v252, 18
	v_readlane_b32 s6, v251, 4
	s_mul_i32 s0, s43, s0
	v_readlane_b32 s7, v251, 5
	s_mul_hi_u32 s1, s43, s6
	s_add_i32 s1, s1, s0
	s_mul_i32 s0, s43, s6
	v_readlane_b32 s6, v252, 36
	v_readlane_b32 s7, v252, 37
	s_add_u32 s20, s0, s6
	s_addc_u32 s21, s1, s7
	v_mov_b64_e32 v[2:3], 0x1600
	v_cmp_lt_i64_e64 s[0:1], s[20:21], v[2:3]
	v_mov_b64_e32 v[2:3], 0x15ff
	v_cmp_gt_i64_e32 vcc, s[20:21], v[2:3]
	s_cbranch_vccnz .Lzs_0
	s_ashr_i32 s6, s20, 31
	s_lshr_b32 s6, s6, 29
	v_mfma_f32_32x32x16_bf16 v[18:33], v[246:249], v[246:249], 0
	s_add_i32 s6, s20, s6
	s_ashr_i32 s7, s6, 3
	s_and_b32 s6, s6, -8
	s_sub_i32 s6, s20, s6
	s_cmp_lt_i32 s6, 0
	s_movk_i32 s10, 0x2c1
	v_mfma_f32_32x32x16_bf16 v[34:49], v[246:249], v[246:249], 0
	s_cselect_b32 s10, s10, 0x2c0
	s_mul_i32 s6, s6, s10
	s_add_i32 s6, s6, s7
	s_mul_hi_i32 s7, s6, 0x2e8ba2e9
	s_lshr_b32 s10, s7, 31
	s_ashr_i32 s7, s7, 5
	v_mfma_f32_32x32x16_bf16 v[50:65], v[246:249], v[246:249], 0
	s_add_i32 s7, s7, s10
	s_lshl_b32 s10, s7, 3
	s_sub_i32 s11, 0x100, s10
	s_min_i32 s11, s11, 8
	s_abs_i32 s16, s11
	v_cvt_f32_u32_e32 v2, s16
	v_mfma_f32_32x32x16_bf16 v[66:81], v[246:249], v[246:249], 0
	s_sub_i32 s18, 0, s16
	s_mulk_i32 s7, 0xb0
	s_sub_i32 s6, s6, s7
	v_rcp_iflag_f32_e32 v2, v2
	s_abs_i32 s7, s6
	s_xor_b32 s17, s6, s11
	v_mfma_f32_32x32x16_bf16 v[82:97], v[246:249], v[246:249], 0
	s_ashr_i32 s17, s17, 31
	v_mul_f32_e32 v2, 0x4f7ffffe, v2
	v_cvt_u32_f32_e32 v2, v2
	s_nop 0
	v_readfirstlane_b32 s19, v2
	s_mul_i32 s18, s18, s19
	v_mfma_f32_32x32x16_bf16 v[98:113], v[246:249], v[246:249], 0
	s_mul_hi_u32 s18, s19, s18
	s_add_i32 s19, s19, s18
	s_mul_hi_u32 s18, s7, s19
	s_mul_i32 s19, s18, s16
	s_sub_i32 s7, s7, s19
	s_add_i32 s20, s18, 1
	v_mfma_f32_32x32x16_bf16 v[114:129], v[246:249], v[246:249], 0
	s_sub_i32 s19, s7, s16
	s_cmp_ge_u32 s7, s16
	s_cselect_b32 s18, s20, s18
	s_cselect_b32 s7, s19, s7
	s_add_i32 s19, s18, 1
	s_cmp_ge_u32 s7, s16
	s_cselect_b32 s7, s19, s18
	s_xor_b32 s7, s7, s17
	s_sub_i32 s16, s7, s17
	s_mul_i32 s7, s16, s11
	s_sub_i32 s6, s6, s7
	s_add_i32 s18, s10, s6
	s_branch .LBB0_164
.Lzs_0:
	v_mfma_f32_32x32x16_bf16 v[18:33], v[246:249], v[246:249], 0
	v_mfma_f32_32x32x16_bf16 v[34:49], v[246:249], v[246:249], 0
	v_mfma_f32_32x32x16_bf16 v[50:65], v[246:249], v[246:249], 0
	v_mfma_f32_32x32x16_bf16 v[66:81], v[246:249], v[246:249], 0
	v_mfma_f32_32x32x16_bf16 v[82:97], v[246:249], v[246:249], 0
	v_mfma_f32_32x32x16_bf16 v[98:113], v[246:249], v[246:249], 0
	v_mfma_f32_32x32x16_bf16 v[114:129], v[246:249], v[246:249], 0
.LBB0_164:
	s_ashr_i32 s19, s18, 31
	s_lshl_b64 s[6:7], s[18:19], 19
	s_add_u32 s20, s38, s6
	s_addc_u32 s21, s39, s7
	s_and_b64 s[6:7], s[0:1], exec
	s_cselect_b32 s19, s21, s25
	s_cselect_b32 s45, s20, s24
	s_ashr_i32 s17, s16, 31
	s_lshl_b64 s[6:7], s[16:17], 19
	v_readlane_b32 s10, v252, 43
	v_readlane_b32 s11, v252, 44
	s_add_u32 s22, s10, s6
	s_addc_u32 s23, s11, s7
	s_and_b64 s[6:7], s[0:1], exec
	s_cselect_b32 s10, s23, s27
	s_cselect_b32 s11, s22, s26
	s_add_u32 s24, s24, 0x40080
	s_addc_u32 s25, s25, 0
	s_add_u32 s17, s26, 0x100
	v_mov_b32_e32 v2, 0
	s_addc_u32 s46, s27, 0
	s_mov_b32 s47, -2
	v_mov_b32_e32 v3, v2
	v_mov_b32_e32 v4, v2
	v_mov_b32_e32 v5, v2
	v_mov_b32_e32 v6, v2
	v_mov_b32_e32 v7, v2
	v_mov_b32_e32 v8, v2
	v_mov_b32_e32 v9, v2
	v_mov_b32_e32 v10, v2
	v_mov_b32_e32 v11, v2
	v_mov_b32_e32 v12, v2
	v_mov_b32_e32 v13, v2
	v_mov_b32_e32 v14, v2
	v_mov_b32_e32 v15, v2
	v_mov_b32_e32 v16, v2
	v_mov_b32_e32 v17, v2

;     __device__ __forceinline__ bool next(int i, Unit& u) const {
;         const long L = (long)i * G + c; if (L >= nwg) return false;
;         int wgid = (int)L; { const int q = nwg / NXCD, r = nwg % NXCD, xcd = wgid % NXCD, off = wgid / NXCD; wgid = (xcd < r ? xcd * (q + 1) : r * (q + 1) + (xcd - r) * q) + off; }
;         const int nig = WGM * nN, gid = wgid / nig, fm = gid * WGM, gsz = (nM - fm) < WGM ? (nM - fm) : WGM;
;         u.pm = fm + ((wgid % nig) % gsz); u.pn = (wgid % nig) / gsz; return true;
;     }
; template <class Epi>
; __device__ __forceinline__ void gemm_phase(LAS unsigned char* lds, int wave_s, const Gemm g, const StaticOrder S, const Epi E) {
;     ...
;         const bool has_next = S.next(ui + 1, nxt);
.LBB0_230:
	v_mov_b32_e32 v246, 0
	v_mov_b32_e32 v247, 0
	v_mov_b32_e32 v248, 0
	v_mov_b32_e32 v249, 0
	s_add_i32 s28, s28, 1
	v_readlane_b32 s0, v252, 18
	v_readlane_b32 s6, v251, 4
	s_mul_i32 s0, s28, s0
	v_readlane_b32 s7, v251, 5
	s_mul_hi_u32 s1, s28, s6
	s_add_i32 s1, s1, s0
	s_mul_i32 s0, s28, s6
	v_readlane_b32 s6, v252, 36
	v_readlane_b32 s7, v252, 37
	s_add_u32 s16, s0, s6
	s_addc_u32 s17, s1, s7
	s_waitcnt lgkmcnt(0)
	v_mov_b64_e32 v[2:3], 0x400
	v_cmp_gt_i64_e32 vcc, s[16:17], v[204:205]
	v_cmp_lt_i64_e64 s[0:1], s[16:17], v[2:3]
	s_cbranch_vccnz .Lzs_1
	s_ashr_i32 s6, s16, 31
	s_lshr_b32 s6, s6, 29
	s_add_i32 s6, s16, s6
	s_and_b32 s7, s6, -8
	s_sub_i32 s7, s16, s7
	s_cmp_gt_i32 s7, -1
	s_mov_b64 s[16:17], -1
	s_cbranch_scc0 .LBB0_233
	s_lshl_b32 s10, s7, 7
	s_mov_b64 s[16:17], 0

;     __device__ __forceinline__ bool next(int i, Unit& u) const {
;         const long L = (long)i * G + c; if (L >= nwg) return false;
;         int wgid = (int)L; { const int q = nwg / NXCD, r = nwg % NXCD, xcd = wgid % NXCD, off = wgid / NXCD; wgid = (xcd < r ? xcd * (q + 1) : r * (q + 1) + (xcd - r) * q) + off; }
;         const int nig = WGM * nN, gid = wgid / nig, fm = gid * WGM, gsz = (nM - fm) < WGM ? (nM - fm) : WGM;
;         u.pm = fm + ((wgid % nig) % gsz); u.pn = (wgid % nig) / gsz; return true;
;     }
.LBB0_235:
	s_ashr_i32 s6, s6, 3
	s_add_i32 s6, s10, s6
	v_mfma_f32_32x32x16_bf16 v[18:33], v[246:249], v[246:249], 0
	s_ashr_i32 s7, s6, 31
	s_lshr_b32 s7, s7, 27
	s_add_i32 s7, s6, s7
	s_ashr_i32 s10, s7, 5
	s_lshl_b32 s10, s10, 3
	v_mfma_f32_32x32x16_bf16 v[34:49], v[246:249], v[246:249], 0
	s_sub_i32 s11, 0x100, s10
	s_min_i32 s11, s11, 8
	s_abs_i32 s16, s11
	v_cvt_f32_u32_e32 v2, s16
	s_sub_i32 s18, 0, s16
	v_mfma_f32_32x32x16_bf16 v[50:65], v[246:249], v[246:249], 0
	s_andn2_b32 s7, s7, 31
	s_sub_i32 s6, s6, s7
	v_rcp_iflag_f32_e32 v2, v2
	s_abs_i32 s7, s6
	s_xor_b32 s17, s6, s11
	v_mfma_f32_32x32x16_bf16 v[66:81], v[246:249], v[246:249], 0
	s_ashr_i32 s17, s17, 31
	v_mul_f32_e32 v2, 0x4f7ffffe, v2
	v_cvt_u32_f32_e32 v2, v2
	s_nop 0
	v_readfirstlane_b32 s19, v2
	v_mfma_f32_32x32x16_bf16 v[82:97], v[246:249], v[246:249], 0
	s_mul_i32 s18, s18, s19
	s_mul_hi_u32 s18, s19, s18
	s_add_i32 s19, s19, s18
	s_mul_hi_u32 s18, s7, s19
	s_mul_i32 s19, s18, s16
	v_mfma_f32_32x32x16_bf16 v[98:113], v[246:249], v[246:249], 0
	s_sub_i32 s7, s7, s19
	s_add_i32 s29, s18, 1
	s_sub_i32 s19, s7, s16
	s_cmp_ge_u32 s7, s16
	s_cselect_b32 s18, s29, s18
	v_mfma_f32_32x32x16_bf16 v[114:129], v[246:249], v[246:249], 0
	s_cselect_b32 s7, s19, s7
	s_add_i32 s19, s18, 1
	s_cmp_ge_u32 s7, s16
	s_cselect_b32 s7, s19, s18
	s_xor_b32 s7, s7, s17
	s_sub_i32 s29, s7, s17
	s_mul_i32 s7, s29, s11
	s_sub_i32 s6, s6, s7
	s_add_i32 s30, s10, s6
	s_branch .LBB0_236

; template <class Epi>
; __device__ __forceinline__ void gemm_phase(LAS unsigned char* lds, int wave_s, const Gemm g, const StaticOrder S, const Epi E) {
;     ...
;         const bool has_next = S.next(ui + 1, nxt);
;         const char* nA = has_next ? (const char*)g.A + (size_t)nxt.pm * tstepA : cA; const char* nB = has_next ? (const char*)g.Bt + (size_t)nxt.pn * tstepB : cB;
;     ...
; #pragma unroll
;         for (int a = 0; a < 2; ++a)
; #pragma unroll
;             for (int b = 0; b < 2; ++b)
; #pragma unroll
;                 for (int m = 0; m < 4; ++m)
; #pragma unroll
;                     for (int n = 0; n < 2; ++n) acc[a][b][m][n] = (f32x4){0.f, 0.f, 0.f, 0.f};
.LBB0_240:
	s_add_u32 s10, s14, 0x100
	v_mov_b32_e32 v2, 0
	s_addc_u32 s11, s15, 0
	s_mov_b32 s34, -2
	v_mov_b32_e32 v3, v2
	v_mov_b32_e32 v4, v2
	v_mov_b32_e32 v5, v2
	v_mov_b32_e32 v6, v2
	v_mov_b32_e32 v7, v2
	v_mov_b32_e32 v8, v2
	v_mov_b32_e32 v9, v2
	v_mov_b32_e32 v10, v2
	v_mov_b32_e32 v11, v2
	v_mov_b32_e32 v12, v2
	v_mov_b32_e32 v13, v2
	v_mov_b32_e32 v14, v2
	v_mov_b32_e32 v15, v2
	v_mov_b32_e32 v16, v2
	v_mov_b32_e32 v17, v2

;     __device__ __forceinline__ bool next(int i, Unit& u) const {
;         const long L = (long)i * G + c; if (L >= nwg) return false;
;         int wgid = (int)L; { const int q = nwg / NXCD, r = nwg % NXCD, xcd = wgid % NXCD, off = wgid / NXCD; wgid = (xcd < r ? xcd * (q + 1) : r * (q + 1) + (xcd - r) * q) + off; }
;         const int nig = WGM * nN, gid = wgid / nig, fm = gid * WGM, gsz = (nM - fm) < WGM ? (nM - fm) : WGM;
;         u.pm = fm + ((wgid % nig) % gsz); u.pn = (wgid % nig) / gsz; return true;
;     }
; template <class Epi>
; __device__ __forceinline__ void gemm_phase(LAS unsigned char* lds, int wave_s, const Gemm g, const StaticOrder S, const Epi E) {
;     ...
;         const bool has_next = S.next(ui + 1, nxt);
.LBB0_325:
	v_mov_b32_e32 v246, 0
	v_mov_b32_e32 v247, 0
	v_mov_b32_e32 v248, 0
	v_mov_b32_e32 v249, 0
	s_add_i32 s18, s18, 1
	v_readlane_b32 s6, v252, 18
	s_mul_i32 s6, s18, s6
	s_mul_hi_u32 s7, s18, s30
	s_add_i32 s7, s7, s6
	s_mul_i32 s6, s18, s30
	v_readlane_b32 s10, v252, 36
	v_readlane_b32 s11, v252, 37
	s_add_u32 s24, s6, s10
	s_addc_u32 s25, s7, s11
	v_mov_b64_e32 v[2:3], 0x1080
	v_cmp_lt_i64_e64 s[48:49], s[24:25], v[2:3]
	v_mov_b64_e32 v[2:3], 0x107f
	v_cmp_gt_i64_e32 vcc, s[24:25], v[2:3]
	s_cbranch_vccnz .Lzs_2
	s_ashr_i32 s6, s24, 31
	s_lshr_b32 s6, s6, 29
	v_mfma_f32_32x32x16_bf16 v[18:33], v[246:249], v[246:249], 0
	s_add_i32 s6, s24, s6
	s_ashr_i32 s7, s6, 3
	s_and_b32 s6, s6, -8
	s_sub_i32 s6, s24, s6
	s_cmp_lt_i32 s6, 0
	s_cselect_b32 s10, s94, 0x210
	v_mfma_f32_32x32x16_bf16 v[34:49], v[246:249], v[246:249], 0
	s_mul_i32 s6, s6, s10
	s_add_i32 s6, s6, s7
	s_mul_hi_i32 s7, s6, 0x3e0f83e1
	s_lshr_b32 s10, s7, 31
	s_ashr_i32 s7, s7, 6
	s_add_i32 s7, s7, s10
	v_mfma_f32_32x32x16_bf16 v[50:65], v[246:249], v[246:249], 0
	s_lshl_b32 s10, s7, 3
	s_sub_i32 s11, 0x80, s10
	s_min_i32 s11, s11, 8
	s_abs_i32 s20, s11
	v_cvt_f32_u32_e32 v0, s20
	s_sub_i32 s22, 0, s20
	v_mfma_f32_32x32x16_bf16 v[66:81], v[246:249], v[246:249], 0
	s_mulk_i32 s7, 0x108
	s_sub_i32 s6, s6, s7
	v_rcp_iflag_f32_e32 v0, v0
	s_abs_i32 s7, s6
	s_xor_b32 s21, s6, s11
	s_ashr_i32 s21, s21, 31
	v_mfma_f32_32x32x16_bf16 v[82:97], v[246:249], v[246:249], 0
	v_mul_f32_e32 v0, 0x4f7ffffe, v0
	v_cvt_u32_f32_e32 v0, v0
	s_nop 0
	v_readfirstlane_b32 s23, v0
	s_mul_i32 s22, s22, s23
	s_mul_hi_u32 s22, s23, s22
	v_mfma_f32_32x32x16_bf16 v[98:113], v[246:249], v[246:249], 0
	s_add_i32 s23, s23, s22
	s_mul_hi_u32 s22, s7, s23
	s_mul_i32 s23, s22, s20
	s_sub_i32 s7, s7, s23
	s_add_i32 s24, s22, 1
	s_sub_i32 s23, s7, s20
	v_mfma_f32_32x32x16_bf16 v[114:129], v[246:249], v[246:249], 0
	s_cmp_ge_u32 s7, s20
	s_cselect_b32 s22, s24, s22
	s_cselect_b32 s7, s23, s7
	s_add_i32 s23, s22, 1
	s_cmp_ge_u32 s7, s20
	s_cselect_b32 s7, s23, s22
	s_xor_b32 s7, s7, s21
	s_sub_i32 s20, s7, s21
	s_mul_i32 s7, s20, s11
	s_sub_i32 s6, s6, s7
	s_add_i32 s22, s10, s6
	s_branch .LBB0_327

; template <class Epi>
; __device__ __forceinline__ void gemm_phase(LAS unsigned char* lds, int wave_s, const Gemm g, const StaticOrder S, const Epi E) {
;     ...
;         const bool has_next = S.next(ui + 1, nxt);
;         const char* nA = has_next ? (const char*)g.A + (size_t)nxt.pm * tstepA : cA; const char* nB = has_next ? (const char*)g.Bt + (size_t)nxt.pn * tstepB : cB;
;     ...
; #pragma unroll
;         for (int a = 0; a < 2; ++a)
; #pragma unroll
;             for (int b = 0; b < 2; ++b)
; #pragma unroll
;                 for (int m = 0; m < 4; ++m)
; #pragma unroll
;                     for (int n = 0; n < 2; ++n) acc[a][b][m][n] = (f32x4){0.f, 0.f, 0.f, 0.f};
.LBB0_327:
	s_ashr_i32 s23, s22, 31
	s_lshl_b64 s[6:7], s[22:23], 19
	s_add_u32 s24, s50, s6
	s_addc_u32 s25, s51, s7
	s_and_b64 s[6:7], s[48:49], exec
	s_cselect_b32 s23, s25, s1
	s_cselect_b32 s34, s24, s0
	s_ashr_i32 s21, s20, 31
	s_lshl_b64 s[6:7], s[20:21], 19
	v_readlane_b32 s10, v250, 33
	v_readlane_b32 s11, v250, 34
	s_add_u32 s26, s10, s6
	s_addc_u32 s27, s11, s7
	s_and_b64 s[6:7], s[48:49], exec
	s_cselect_b32 s10, s27, s29
	s_cselect_b32 s11, s26, s28
	s_add_u32 s0, s0, 0x40080
	s_addc_u32 s1, s1, 0
	s_add_u32 s21, s28, 0x100
	v_mov_b32_e32 v2, 0
	s_addc_u32 s35, s29, 0
	s_mov_b32 s50, -2
	v_mov_b32_e32 v3, v2
	v_mov_b32_e32 v4, v2
	v_mov_b32_e32 v5, v2
	v_mov_b32_e32 v6, v2
	v_mov_b32_e32 v7, v2
	v_mov_b32_e32 v8, v2
	v_mov_b32_e32 v9, v2
	v_mov_b32_e32 v10, v2
	s_waitcnt lgkmcnt(0)
	v_mov_b32_e32 v11, v2
	v_mov_b32_e32 v12, v2
	v_mov_b32_e32 v13, v2
	v_mov_b32_e32 v14, v2
	v_mov_b32_e32 v15, v2
	v_mov_b32_e32 v16, v2
	v_mov_b32_e32 v17, v2

;     __device__ __forceinline__ bool next(int i, Unit& u) const {
;         const long L = (long)i * G + c; if (L >= nwg) return false;
;         int wgid = (int)L; { const int q = nwg / NXCD, r = nwg % NXCD, xcd = wgid % NXCD, off = wgid / NXCD; wgid = (xcd < r ? xcd * (q + 1) : r * (q + 1) + (xcd - r) * q) + off; }
;         const int nig = WGM * nN, gid = wgid / nig, fm = gid * WGM, gsz = (nM - fm) < WGM ? (nM - fm) : WGM;
;         u.pm = fm + ((wgid % nig) % gsz); u.pn = (wgid % nig) / gsz; return true;
;     }
; template <class Epi>
; __device__ __forceinline__ void gemm_phase(LAS unsigned char* lds, int wave_s, const Gemm g, const StaticOrder S, const Epi E) {
;     ...
;         const bool has_next = S.next(ui + 1, nxt);
.LBB0_558:
	v_mov_b32_e32 v246, 0
	v_mov_b32_e32 v247, 0
	v_mov_b32_e32 v248, 0
	v_mov_b32_e32 v249, 0
	s_add_i32 s37, s37, 1
	v_readlane_b32 s0, v252, 18
	v_readlane_b32 s6, v251, 4
	s_mul_i32 s0, s37, s0
	v_readlane_b32 s7, v251, 5
	s_mul_hi_u32 s1, s37, s6
	s_add_i32 s1, s1, s0
	s_mul_i32 s0, s37, s6
	v_readlane_b32 s6, v252, 36
	v_readlane_b32 s7, v252, 37
	s_add_u32 s16, s0, s6
	s_addc_u32 s17, s1, s7
	v_mov_b64_e32 v[2:3], 0x300
	v_cmp_lt_i64_e64 s[0:1], s[16:17], v[2:3]
	v_mov_b64_e32 v[2:3], 0x2ff
	v_cmp_gt_i64_e32 vcc, s[16:17], v[2:3]
	s_cbranch_vccnz .Lzs_3
	s_ashr_i32 s6, s16, 31
	s_lshr_b32 s6, s6, 29
	v_mfma_f32_32x32x16_bf16 v[18:33], v[246:249], v[246:249], 0
	s_add_i32 s6, s16, s6
	s_ashr_i32 s7, s6, 3
	s_and_b32 s6, s6, -8
	s_sub_i32 s6, s16, s6
	s_cmp_lt_i32 s6, 0
	s_movk_i32 s10, 0x61
	v_mfma_f32_32x32x16_bf16 v[34:49], v[246:249], v[246:249], 0
	s_cselect_b32 s10, s10, 0x60
	s_mul_i32 s6, s6, s10
	s_add_i32 s6, s6, s7
	s_mul_hi_i32 s7, s6, 0x2aaaaaab
	s_lshr_b32 s10, s7, 31
	s_ashr_i32 s7, s7, 3
	v_mfma_f32_32x32x16_bf16 v[50:65], v[246:249], v[246:249], 0
	s_add_i32 s7, s7, s10
	s_lshl_b32 s10, s7, 3
	s_sub_i32 s11, 0x80, s10
	s_min_i32 s11, s11, 8
	s_abs_i32 s16, s11
	v_cvt_f32_u32_e32 v0, s16
	v_mfma_f32_32x32x16_bf16 v[66:81], v[246:249], v[246:249], 0
	s_sub_i32 s22, 0, s16
	s_mul_i32 s7, s7, 48
	s_sub_i32 s6, s6, s7
	v_rcp_iflag_f32_e32 v0, v0
	s_abs_i32 s7, s6
	s_xor_b32 s17, s6, s11
	v_mfma_f32_32x32x16_bf16 v[82:97], v[246:249], v[246:249], 0
	s_ashr_i32 s17, s17, 31
	v_mul_f32_e32 v0, 0x4f7ffffe, v0
	v_cvt_u32_f32_e32 v0, v0
	s_nop 0
	v_readfirstlane_b32 s23, v0
	s_mul_i32 s22, s22, s23
	v_mfma_f32_32x32x16_bf16 v[98:113], v[246:249], v[246:249], 0
	s_mul_hi_u32 s22, s23, s22
	s_add_i32 s23, s23, s22
	s_mul_hi_u32 s22, s7, s23
	s_mul_i32 s23, s22, s16
	s_sub_i32 s7, s7, s23
	s_add_i32 s24, s22, 1
	v_mfma_f32_32x32x16_bf16 v[114:129], v[246:249], v[246:249], 0
	s_sub_i32 s23, s7, s16
	s_cmp_ge_u32 s7, s16
	s_cselect_b32 s22, s24, s22
	s_cselect_b32 s7, s23, s7
	s_add_i32 s23, s22, 1
	s_cmp_ge_u32 s7, s16
	s_cselect_b32 s7, s23, s22
	s_xor_b32 s7, s7, s17
	s_sub_i32 s38, s7, s17
	s_mul_i32 s7, s38, s11
	s_sub_i32 s6, s6, s7
	s_add_i32 s39, s10, s6
	s_branch .LBB0_560

; template <class Epi>
; __device__ __forceinline__ void gemm_phase(LAS unsigned char* lds, int wave_s, const Gemm g, const StaticOrder S, const Epi E) {
;     ...
;         const bool has_next = S.next(ui + 1, nxt);
;         const char* nA = has_next ? (const char*)g.A + (size_t)nxt.pm * tstepA : cA; const char* nB = has_next ? (const char*)g.Bt + (size_t)nxt.pn * tstepB : cB;
;     ...
; #pragma unroll
;         for (int a = 0; a < 2; ++a)
; #pragma unroll
;             for (int b = 0; b < 2; ++b)
; #pragma unroll
;                 for (int m = 0; m < 4; ++m)
; #pragma unroll
;                     for (int n = 0; n < 2; ++n) acc[a][b][m][n] = (f32x4){0.f, 0.f, 0.f, 0.f};
.LBB0_564:
	s_add_u32 s10, s20, 0x100
	v_mov_b32_e32 v2, 0
	s_addc_u32 s11, s21, 0
	s_mov_b32 s50, -2
	v_mov_b32_e32 v3, v2
	v_mov_b32_e32 v4, v2
	v_mov_b32_e32 v5, v2
	v_mov_b32_e32 v6, v2
	v_mov_b32_e32 v7, v2
	v_mov_b32_e32 v8, v2
	v_mov_b32_e32 v9, v2
	v_mov_b32_e32 v10, v2
	v_mov_b32_e32 v11, v2
	v_mov_b32_e32 v12, v2
	v_mov_b32_e32 v13, v2
	v_mov_b32_e32 v14, v2
	v_mov_b32_e32 v15, v2
	v_mov_b32_e32 v16, v2
	v_mov_b32_e32 v17, v2

;     __device__ __forceinline__ bool next(int i, Unit& u) const {
;         const long L = (long)i * G + c; if (L >= nwg) return false;
;         int wgid = (int)L; { const int q = nwg / NXCD, r = nwg % NXCD, xcd = wgid % NXCD, off = wgid / NXCD; wgid = (xcd < r ? xcd * (q + 1) : r * (q + 1) + (xcd - r) * q) + off; }
;         const int nig = WGM * nN, gid = wgid / nig, fm = gid * WGM, gsz = (nM - fm) < WGM ? (nM - fm) : WGM;
;         u.pm = fm + ((wgid % nig) % gsz); u.pn = (wgid % nig) / gsz; return true;
;     }
; template <class Epi>
; __device__ __forceinline__ void gemm_phase(LAS unsigned char* lds, int wave_s, const Gemm g, const StaticOrder S, const Epi E) {
;     ...
;         const bool has_next = S.next(ui + 1, nxt);
.LBB0_626:
	v_mov_b32_e32 v246, 0
	v_mov_b32_e32 v247, 0
	v_mov_b32_e32 v248, 0
	v_mov_b32_e32 v249, 0
	s_add_i32 s52, s52, 1
	v_readlane_b32 s0, v252, 18
	s_mul_i32 s0, s52, s0
	s_mul_hi_u32 s1, s52, s30
	s_add_i32 s1, s1, s0
	s_mul_i32 s0, s52, s30
	v_readlane_b32 s6, v252, 36
	v_readlane_b32 s7, v252, 37
	s_add_u32 s18, s0, s6
	s_addc_u32 s19, s1, s7
	v_mov_b64_e32 v[2:3], 0x400
	v_cmp_gt_i64_e32 vcc, s[18:19], v[204:205]
	v_cmp_lt_i64_e64 s[0:1], s[18:19], v[2:3]
	s_cbranch_vccnz .Lzs_4
	s_ashr_i32 s6, s18, 31
	s_lshr_b32 s6, s6, 29
	s_add_i32 s6, s18, s6
	s_and_b32 s7, s6, -8
	s_sub_i32 s7, s18, s7
	s_cmp_gt_i32 s7, -1
	s_mov_b64 s[16:17], -1
	s_cbranch_scc0 .LBB0_629
	s_lshl_b32 s10, s7, 7
	s_mov_b64 s[16:17], 0

;     __device__ __forceinline__ bool next(int i, Unit& u) const {
;         const long L = (long)i * G + c; if (L >= nwg) return false;
;         int wgid = (int)L; { const int q = nwg / NXCD, r = nwg % NXCD, xcd = wgid % NXCD, off = wgid / NXCD; wgid = (xcd < r ? xcd * (q + 1) : r * (q + 1) + (xcd - r) * q) + off; }
;         const int nig = WGM * nN, gid = wgid / nig, fm = gid * WGM, gsz = (nM - fm) < WGM ? (nM - fm) : WGM;
;         u.pm = fm + ((wgid % nig) % gsz); u.pn = (wgid % nig) / gsz; return true;
;     }
.LBB0_631:
	s_ashr_i32 s6, s6, 3
	s_add_i32 s6, s10, s6
	v_mfma_f32_32x32x16_bf16 v[18:33], v[246:249], v[246:249], 0
	s_ashr_i32 s7, s6, 31
	s_lshr_b32 s7, s7, 26
	s_add_i32 s7, s6, s7
	s_ashr_i32 s10, s7, 6
	s_lshl_b32 s10, s10, 3
	v_mfma_f32_32x32x16_bf16 v[34:49], v[246:249], v[246:249], 0
	s_sub_i32 s11, 0x80, s10
	s_min_i32 s11, s11, 8
	s_abs_i32 s12, s11
	v_cvt_f32_u32_e32 v2, s12
	s_sub_i32 s16, 0, s12
	v_mfma_f32_32x32x16_bf16 v[50:65], v[246:249], v[246:249], 0
	s_andn2_b32 s7, s7, 63
	s_sub_i32 s6, s6, s7
	v_rcp_iflag_f32_e32 v2, v2
	s_abs_i32 s7, s6
	s_xor_b32 s13, s6, s11
	v_mfma_f32_32x32x16_bf16 v[66:81], v[246:249], v[246:249], 0
	s_ashr_i32 s13, s13, 31
	v_mul_f32_e32 v2, 0x4f7ffffe, v2
	v_cvt_u32_f32_e32 v2, v2
	s_nop 0
	v_readfirstlane_b32 s17, v2
	v_mfma_f32_32x32x16_bf16 v[82:97], v[246:249], v[246:249], 0
	s_mul_i32 s16, s16, s17
	s_mul_hi_u32 s16, s17, s16
	s_add_i32 s17, s17, s16
	s_mul_hi_u32 s16, s7, s17
	s_mul_i32 s17, s16, s12
	v_mfma_f32_32x32x16_bf16 v[98:113], v[246:249], v[246:249], 0
	s_sub_i32 s7, s7, s17
	s_add_i32 s18, s16, 1
	s_sub_i32 s17, s7, s12
	s_cmp_ge_u32 s7, s12
	s_cselect_b32 s16, s18, s16
	v_mfma_f32_32x32x16_bf16 v[114:129], v[246:249], v[246:249], 0
	s_cselect_b32 s7, s17, s7
	s_add_i32 s17, s16, 1
	s_cmp_ge_u32 s7, s12
	s_cselect_b32 s7, s17, s16
	s_xor_b32 s7, s7, s13
	s_sub_i32 s16, s7, s13
	s_mul_i32 s7, s16, s11
	s_sub_i32 s6, s6, s7
	s_add_i32 s94, s10, s6
	s_branch .LBB0_632

; template <class Epi>
; __device__ __forceinline__ void gemm_phase(LAS unsigned char* lds, int wave_s, const Gemm g, const StaticOrder S, const Epi E) {
;     ...
;         const bool has_next = S.next(ui + 1, nxt);
;         const char* nA = has_next ? (const char*)g.A + (size_t)nxt.pm * tstepA : cA; const char* nB = has_next ? (const char*)g.Bt + (size_t)nxt.pn * tstepB : cB;
;     ...
; #pragma unroll
;         for (int a = 0; a < 2; ++a)
; #pragma unroll
;             for (int b = 0; b < 2; ++b)
; #pragma unroll
;                 for (int m = 0; m < 4; ++m)
; #pragma unroll
;                     for (int n = 0; n < 2; ++n) acc[a][b][m][n] = (f32x4){0.f, 0.f, 0.f, 0.f};
.LBB0_634:
	s_ashr_i32 s17, s16, 31
	s_lshl_b64 s[6:7], s[16:17], 17
	v_readlane_b32 s10, v255, 55
	v_readlane_b32 s11, v255, 56
	s_add_u32 s20, s10, s6
	s_addc_u32 s21, s11, s7
	s_and_b64 s[0:1], s[0:1], exec
	v_mov_b32_e32 v2, 0
	s_cselect_b32 s17, s21, s23
	s_cselect_b32 s10, s20, s22
	s_mov_b32 s11, 0
	s_mov_b64 s[0:1], -1
	s_mov_b64 s[26:27], 0
	v_mov_b32_e32 v3, v2
	v_mov_b32_e32 v4, v2
	v_mov_b32_e32 v5, v2
	v_mov_b32_e32 v6, v2
	v_mov_b32_e32 v7, v2
	v_mov_b32_e32 v8, v2
	v_mov_b32_e32 v9, v2
	v_mov_b32_e32 v10, v2
	v_mov_b32_e32 v11, v2
	v_mov_b32_e32 v12, v2
	v_mov_b32_e32 v13, v2
	v_mov_b32_e32 v14, v2
	v_mov_b32_e32 v15, v2
	v_mov_b32_e32 v16, v2
	v_mov_b32_e32 v17, v2

;     __device__ __forceinline__ bool next(int i, Unit& u) const {
;         const long L = (long)i * G + c; if (L >= nwg) return false;
;         int wgid = (int)L; { const int q = nwg / NXCD, r = nwg % NXCD, xcd = wgid % NXCD, off = wgid / NXCD; wgid = (xcd < r ? xcd * (q + 1) : r * (q + 1) + (xcd - r) * q) + off; }
;         const int nig = WGM * nN, gid = wgid / nig, fm = gid * WGM, gsz = (nM - fm) < WGM ? (nM - fm) : WGM;
;         u.pm = fm + ((wgid % nig) % gsz); u.pn = (wgid % nig) / gsz; return true;
;     }
; template <class Epi>
; __device__ __forceinline__ void gemm_phase(LAS unsigned char* lds, int wave_s, const Gemm g, const StaticOrder S, const Epi E) {
;     ...
;         const bool has_next = S.next(ui + 1, nxt);
.LBB0_1059:
	v_mov_b32_e32 v246, 0
	v_mov_b32_e32 v247, 0
	v_mov_b32_e32 v248, 0
	v_mov_b32_e32 v249, 0
	s_add_i32 s51, s51, 1
	v_readlane_b32 s0, v252, 18
	s_mul_i32 s0, s51, s0
	s_mul_hi_u32 s1, s51, s30
	s_add_i32 s1, s1, s0
	s_mul_i32 s0, s51, s30
	v_readlane_b32 s6, v252, 36
	v_readlane_b32 s7, v252, 37
	s_add_u32 s22, s0, s6
	s_addc_u32 s23, s1, s7
	s_waitcnt lgkmcnt(0)
	v_mov_b64_e32 v[2:3], 0x200
	v_cmp_lt_i64_e64 s[0:1], s[22:23], v[2:3]
	v_mov_b64_e32 v[2:3], 0x1ff
	v_cmp_gt_i64_e32 vcc, s[22:23], v[2:3]
	s_cbranch_vccnz .Lzs_5
	s_ashr_i32 s6, s22, 31
	s_lshr_b32 s6, s6, 29
	s_add_i32 s6, s22, s6
	s_and_b32 s7, s6, -8
	s_sub_i32 s7, s22, s7
	s_cmp_gt_i32 s7, -1
	s_mov_b64 s[20:21], -1
	s_cbranch_scc0 .LBB0_1062
	s_lshl_b32 s10, s7, 6
	s_mov_b64 s[20:21], 0

;     __device__ __forceinline__ bool next(int i, Unit& u) const {
;         const long L = (long)i * G + c; if (L >= nwg) return false;
;         int wgid = (int)L; { const int q = nwg / NXCD, r = nwg % NXCD, xcd = wgid % NXCD, off = wgid / NXCD; wgid = (xcd < r ? xcd * (q + 1) : r * (q + 1) + (xcd - r) * q) + off; }
;         const int nig = WGM * nN, gid = wgid / nig, fm = gid * WGM, gsz = (nM - fm) < WGM ? (nM - fm) : WGM;
;         u.pm = fm + ((wgid % nig) % gsz); u.pn = (wgid % nig) / gsz; return true;
;     }
.LBB0_1064:
	s_ashr_i32 s6, s6, 3
	s_add_i32 s6, s10, s6
	v_mfma_f32_32x32x16_bf16 v[18:33], v[246:249], v[246:249], 0
	s_ashr_i32 s7, s6, 31
	s_lshr_b32 s7, s7, 27
	s_add_i32 s7, s6, s7
	s_ashr_i32 s10, s7, 5
	s_lshl_b32 s10, s10, 3
	v_mfma_f32_32x32x16_bf16 v[34:49], v[246:249], v[246:249], 0
	s_sub_i32 s11, 0x80, s10
	s_min_i32 s11, s11, 8
	s_abs_i32 s20, s11
	v_cvt_f32_u32_e32 v2, s20
	s_sub_i32 s22, 0, s20
	v_mfma_f32_32x32x16_bf16 v[50:65], v[246:249], v[246:249], 0
	s_andn2_b32 s7, s7, 31
	s_sub_i32 s6, s6, s7
	v_rcp_iflag_f32_e32 v2, v2
	s_abs_i32 s7, s6
	s_xor_b32 s21, s6, s11
	v_mfma_f32_32x32x16_bf16 v[66:81], v[246:249], v[246:249], 0
	s_ashr_i32 s21, s21, 31
	v_mul_f32_e32 v2, 0x4f7ffffe, v2
	v_cvt_u32_f32_e32 v2, v2
	s_nop 0
	v_readfirstlane_b32 s23, v2
	v_mfma_f32_32x32x16_bf16 v[82:97], v[246:249], v[246:249], 0
	s_mul_i32 s22, s22, s23
	s_mul_hi_u32 s22, s23, s22
	s_add_i32 s23, s23, s22
	s_mul_hi_u32 s22, s7, s23
	s_mul_i32 s23, s22, s20
	v_mfma_f32_32x32x16_bf16 v[98:113], v[246:249], v[246:249], 0
	s_sub_i32 s7, s7, s23
	s_add_i32 s24, s22, 1
	s_sub_i32 s23, s7, s20
	s_cmp_ge_u32 s7, s20
	s_cselect_b32 s22, s24, s22
	v_mfma_f32_32x32x16_bf16 v[114:129], v[246:249], v[246:249], 0
	s_cselect_b32 s7, s23, s7
	s_add_i32 s23, s22, 1
	s_cmp_ge_u32 s7, s20
	s_cselect_b32 s7, s23, s22
	s_xor_b32 s7, s7, s21
	s_sub_i32 s20, s7, s21
	s_mul_i32 s7, s20, s11
	s_sub_i32 s6, s6, s7
	s_add_i32 s54, s10, s6
	s_branch .LBB0_1065

; template <class Epi>
; __device__ __forceinline__ void gemm_phase(LAS unsigned char* lds, int wave_s, const Gemm g, const StaticOrder S, const Epi E) {
;     ...
;         const bool has_next = S.next(ui + 1, nxt);
;         const char* nA = has_next ? (const char*)g.A + (size_t)nxt.pm * tstepA : cA; const char* nB = has_next ? (const char*)g.Bt + (size_t)nxt.pn * tstepB : cB;
;     ...
; #pragma unroll
;         for (int a = 0; a < 2; ++a)
; #pragma unroll
;             for (int b = 0; b < 2; ++b)
; #pragma unroll
;                 for (int m = 0; m < 4; ++m)
; #pragma unroll
;                     for (int n = 0; n < 2; ++n) acc[a][b][m][n] = (f32x4){0.f, 0.f, 0.f, 0.f};
.LBB0_1067:
	s_ashr_i32 s21, s20, 31
	s_lshl_b64 s[6:7], s[20:21], 19
	v_readlane_b32 s10, v253, 6
	v_readlane_b32 s11, v253, 7
	s_add_u32 s24, s10, s6
	s_addc_u32 s25, s11, s7
	s_and_b64 s[0:1], s[0:1], exec
	s_cselect_b32 s10, s25, s29
	s_cselect_b32 s11, s24, s28
	s_add_u32 s21, s28, 0x100
	v_mov_b32_e32 v2, 0
	s_addc_u32 s52, s29, 0
	s_mov_b32 s53, -2
	v_mov_b32_e32 v3, v2
	v_mov_b32_e32 v4, v2
	v_mov_b32_e32 v5, v2
	v_mov_b32_e32 v6, v2
	v_mov_b32_e32 v7, v2
	v_mov_b32_e32 v8, v2
	v_mov_b32_e32 v9, v2
	v_mov_b32_e32 v10, v2
	v_mov_b32_e32 v11, v2
	v_mov_b32_e32 v12, v2
	v_mov_b32_e32 v13, v2
	v_mov_b32_e32 v14, v2
	v_mov_b32_e32 v15, v2
	v_mov_b32_e32 v16, v2
	v_mov_b32_e32 v17, v2

;     __device__ __forceinline__ bool next(int i, Unit& u) const {
;         const long L = (long)i * G + c; if (L >= nwg) return false;
;         int wgid = (int)L; { const int q = nwg / NXCD, r = nwg % NXCD, xcd = wgid % NXCD, off = wgid / NXCD; wgid = (xcd < r ? xcd * (q + 1) : r * (q + 1) + (xcd - r) * q) + off; }
;         const int nig = WGM * nN, gid = wgid / nig, fm = gid * WGM, gsz = (nM - fm) < WGM ? (nM - fm) : WGM;
;         u.pm = fm + ((wgid % nig) % gsz); u.pn = (wgid % nig) / gsz; return true;
;     }
; template <class Epi>
; __device__ __forceinline__ void gemm_phase(LAS unsigned char* lds, int wave_s, const Gemm g, const StaticOrder S, const Epi E) {
;     ...
;         const bool has_next = S.next(ui + 1, nxt);
.LBB0_1148:
	v_mov_b32_e32 v246, 0
	v_mov_b32_e32 v247, 0
	v_mov_b32_e32 v248, 0
	v_mov_b32_e32 v249, 0
	s_add_i32 s38, s38, 1
	v_readlane_b32 s6, v252, 18
	v_readlane_b32 s10, v251, 4
	s_mul_i32 s6, s38, s6
	v_readlane_b32 s11, v251, 5
	s_mul_hi_u32 s7, s38, s10
	s_add_i32 s7, s7, s6
	s_mul_i32 s6, s38, s10
	v_readlane_b32 s10, v252, 36
	v_readlane_b32 s11, v252, 37
	s_add_u32 s18, s6, s10
	s_addc_u32 s19, s7, s11
	v_mov_b64_e32 v[2:3], 0x1600
	v_cmp_lt_i64_e64 s[42:43], s[18:19], v[2:3]
	v_mov_b64_e32 v[2:3], 0x15ff
	v_cmp_gt_i64_e32 vcc, s[18:19], v[2:3]
	s_cbranch_vccnz .Lzs_6
	s_ashr_i32 s6, s18, 31
	s_lshr_b32 s6, s6, 29
	v_mfma_f32_32x32x16_bf16 v[18:33], v[246:249], v[246:249], 0
	s_add_i32 s6, s18, s6
	s_ashr_i32 s7, s6, 3
	s_and_b32 s6, s6, -8
	s_sub_i32 s6, s18, s6
	s_cmp_lt_i32 s6, 0
	s_movk_i32 s10, 0x2c1
	v_mfma_f32_32x32x16_bf16 v[34:49], v[246:249], v[246:249], 0
	s_cselect_b32 s10, s10, 0x2c0
	s_mul_i32 s6, s6, s10
	s_add_i32 s6, s6, s7
	s_mul_hi_i32 s7, s6, 0x2e8ba2e9
	s_lshr_b32 s10, s7, 31
	s_ashr_i32 s7, s7, 5
	v_mfma_f32_32x32x16_bf16 v[50:65], v[246:249], v[246:249], 0
	s_add_i32 s7, s7, s10
	s_lshl_b32 s10, s7, 3
	s_sub_i32 s11, 0x100, s10
	s_min_i32 s11, s11, 8
	s_abs_i32 s14, s11
	v_cvt_f32_u32_e32 v2, s14
	v_mfma_f32_32x32x16_bf16 v[66:81], v[246:249], v[246:249], 0
	s_sub_i32 s16, 0, s14
	s_mulk_i32 s7, 0xb0
	s_sub_i32 s6, s6, s7
	v_rcp_iflag_f32_e32 v2, v2
	s_abs_i32 s7, s6
	s_xor_b32 s15, s6, s11
	v_mfma_f32_32x32x16_bf16 v[82:97], v[246:249], v[246:249], 0
	s_ashr_i32 s15, s15, 31
	v_mul_f32_e32 v2, 0x4f7ffffe, v2
	v_cvt_u32_f32_e32 v2, v2
	s_nop 0
	v_readfirstlane_b32 s17, v2
	s_mul_i32 s16, s16, s17
	v_mfma_f32_32x32x16_bf16 v[98:113], v[246:249], v[246:249], 0
	s_mul_hi_u32 s16, s17, s16
	s_add_i32 s17, s17, s16
	s_mul_hi_u32 s16, s7, s17
	s_mul_i32 s17, s16, s14
	s_sub_i32 s7, s7, s17
	s_add_i32 s18, s16, 1
	v_mfma_f32_32x32x16_bf16 v[114:129], v[246:249], v[246:249], 0
	s_sub_i32 s17, s7, s14
	s_cmp_ge_u32 s7, s14
	s_cselect_b32 s16, s18, s16
	s_cselect_b32 s7, s17, s7
	s_add_i32 s17, s16, 1
	s_cmp_ge_u32 s7, s14
	s_cselect_b32 s7, s17, s16
	s_xor_b32 s7, s7, s15
	s_sub_i32 s14, s7, s15
	s_mul_i32 s7, s14, s11
	s_sub_i32 s6, s6, s7
	s_add_i32 s16, s10, s6
	s_branch .LBB0_1150

; template <class Epi>
; __device__ __forceinline__ void gemm_phase(LAS unsigned char* lds, int wave_s, const Gemm g, const StaticOrder S, const Epi E) {
;     ...
;         const bool has_next = S.next(ui + 1, nxt);
;         const char* nA = has_next ? (const char*)g.A + (size_t)nxt.pm * tstepA : cA; const char* nB = has_next ? (const char*)g.Bt + (size_t)nxt.pn * tstepB : cB;
;     ...
; #pragma unroll
;         for (int a = 0; a < 2; ++a)
; #pragma unroll
;             for (int b = 0; b < 2; ++b)
; #pragma unroll
;                 for (int m = 0; m < 4; ++m)
; #pragma unroll
;                     for (int n = 0; n < 2; ++n) acc[a][b][m][n] = (f32x4){0.f, 0.f, 0.f, 0.f};
.LBB0_1150:
	s_ashr_i32 s17, s16, 31
	s_lshl_b64 s[6:7], s[16:17], 19
	v_readlane_b32 s10, v253, 35
	v_readlane_b32 s11, v253, 36
	s_add_u32 s18, s10, s6
	s_addc_u32 s19, s11, s7
	s_and_b64 s[6:7], s[42:43], exec
	s_cselect_b32 s17, s19, s23
	s_cselect_b32 s40, s18, s22
	s_ashr_i32 s15, s14, 31
	s_lshl_b64 s[6:7], s[14:15], 19
	v_readlane_b32 s10, v252, 54
	v_readlane_b32 s11, v252, 55
	s_add_u32 s20, s10, s6
	s_addc_u32 s21, s11, s7
	s_and_b64 s[6:7], s[42:43], exec
	s_cselect_b32 s10, s21, s25
	s_cselect_b32 s11, s20, s24
	s_add_u32 s22, s22, 0x40080
	s_addc_u32 s23, s23, 0
	s_add_u32 s15, s24, 0x100
	v_mov_b32_e32 v2, 0
	s_addc_u32 s44, s25, 0
	s_mov_b32 s45, -2
	v_mov_b32_e32 v3, v2
	v_mov_b32_e32 v4, v2
	v_mov_b32_e32 v5, v2
	v_mov_b32_e32 v6, v2
	v_mov_b32_e32 v7, v2
	v_mov_b32_e32 v8, v2
	v_mov_b32_e32 v9, v2
	v_mov_b32_e32 v10, v2
	v_mov_b32_e32 v11, v2
	v_mov_b32_e32 v12, v2
	v_mov_b32_e32 v13, v2
	v_mov_b32_e32 v14, v2
	v_mov_b32_e32 v15, v2
	v_mov_b32_e32 v16, v2
	v_mov_b32_e32 v17, v2

;     __device__ __forceinline__ bool next(int i, Unit& u) const {
;         const long L = (long)i * G + c; if (L >= nwg) return false;
;         int wgid = (int)L; { const int q = nwg / NXCD, r = nwg % NXCD, xcd = wgid % NXCD, off = wgid / NXCD; wgid = (xcd < r ? xcd * (q + 1) : r * (q + 1) + (xcd - r) * q) + off; }
;         const int nig = WGM * nN, gid = wgid / nig, fm = gid * WGM, gsz = (nM - fm) < WGM ? (nM - fm) : WGM;
;         u.pm = fm + ((wgid % nig) % gsz); u.pn = (wgid % nig) / gsz; return true;
;     }
; template <class Epi>
; __device__ __forceinline__ void gemm_phase(LAS unsigned char* lds, int wave_s, const Gemm g, const StaticOrder S, const Epi E) {
;     ...
;         const bool has_next = S.next(ui + 1, nxt);
.LBB0_1164:
	v_mov_b32_e32 v246, 0
	v_mov_b32_e32 v247, 0
	v_mov_b32_e32 v248, 0
	v_mov_b32_e32 v249, 0
	s_add_i32 s53, s53, 1
	v_readlane_b32 s0, v252, 18
	s_mul_i32 s0, s53, s0
	s_mul_hi_u32 s1, s53, s30
	s_add_i32 s1, s1, s0
	s_mul_i32 s0, s53, s30
	v_readlane_b32 s6, v252, 36
	v_readlane_b32 s7, v252, 37
	s_add_u32 s18, s0, s6
	s_addc_u32 s19, s1, s7
	v_mov_b64_e32 v[2:3], 0x400
	v_cmp_gt_i64_e32 vcc, s[18:19], v[204:205]
	v_readlane_b32 s20, v255, 8
	v_cmp_lt_i64_e64 s[42:43], s[18:19], v[2:3]
	v_readlane_b32 s21, v255, 9
	s_cbranch_vccnz .Lzs_7
	s_ashr_i32 s0, s18, 31
	s_lshr_b32 s0, s0, 29
	s_add_i32 s0, s18, s0
	s_and_b32 s1, s0, -8
	s_sub_i32 s1, s18, s1
	s_cmp_gt_i32 s1, -1
	s_mov_b64 s[14:15], -1
	s_cbranch_scc0 .LBB0_1167
	s_lshl_b32 s6, s1, 7
	s_mov_b64 s[14:15], 0

;     __device__ __forceinline__ bool next(int i, Unit& u) const {
;         const long L = (long)i * G + c; if (L >= nwg) return false;
;         int wgid = (int)L; { const int q = nwg / NXCD, r = nwg % NXCD, xcd = wgid % NXCD, off = wgid / NXCD; wgid = (xcd < r ? xcd * (q + 1) : r * (q + 1) + (xcd - r) * q) + off; }
;         const int nig = WGM * nN, gid = wgid / nig, fm = gid * WGM, gsz = (nM - fm) < WGM ? (nM - fm) : WGM;
;         u.pm = fm + ((wgid % nig) % gsz); u.pn = (wgid % nig) / gsz; return true;
;     }
.LBB0_1169:
	s_ashr_i32 s0, s0, 3
	s_add_i32 s0, s6, s0
	v_mfma_f32_32x32x16_bf16 v[18:33], v[246:249], v[246:249], 0
	s_ashr_i32 s1, s0, 31
	s_lshr_b32 s1, s1, 27
	s_add_i32 s1, s0, s1
	s_ashr_i32 s6, s1, 5
	s_lshl_b32 s6, s6, 3
	v_mfma_f32_32x32x16_bf16 v[34:49], v[246:249], v[246:249], 0
	s_sub_i32 s7, 0x100, s6
	s_min_i32 s7, s7, 8
	s_abs_i32 s10, s7
	v_cvt_f32_u32_e32 v2, s10
	s_sub_i32 s14, 0, s10
	v_mfma_f32_32x32x16_bf16 v[50:65], v[246:249], v[246:249], 0
	s_andn2_b32 s1, s1, 31
	s_sub_i32 s0, s0, s1
	v_rcp_iflag_f32_e32 v2, v2
	s_abs_i32 s1, s0
	s_xor_b32 s11, s0, s7
	v_mfma_f32_32x32x16_bf16 v[66:81], v[246:249], v[246:249], 0
	s_ashr_i32 s11, s11, 31
	v_mul_f32_e32 v2, 0x4f7ffffe, v2
	v_cvt_u32_f32_e32 v2, v2
	s_nop 0
	v_readfirstlane_b32 s15, v2
	v_mfma_f32_32x32x16_bf16 v[82:97], v[246:249], v[246:249], 0
	s_mul_i32 s14, s14, s15
	s_mul_hi_u32 s14, s15, s14
	s_add_i32 s15, s15, s14
	s_mul_hi_u32 s14, s1, s15
	s_mul_i32 s15, s14, s10
	v_mfma_f32_32x32x16_bf16 v[98:113], v[246:249], v[246:249], 0
	s_sub_i32 s1, s1, s15
	s_add_i32 s16, s14, 1
	s_sub_i32 s15, s1, s10
	s_cmp_ge_u32 s1, s10
	s_cselect_b32 s14, s16, s14
	v_mfma_f32_32x32x16_bf16 v[114:129], v[246:249], v[246:249], 0
	s_cselect_b32 s1, s15, s1
	s_add_i32 s15, s14, 1
	s_cmp_ge_u32 s1, s10
	s_cselect_b32 s1, s15, s14
	s_xor_b32 s1, s1, s11
	s_sub_i32 s14, s1, s11
	s_mul_i32 s1, s14, s7
	s_sub_i32 s0, s0, s1
	s_add_i32 s16, s6, s0
	s_branch .LBB0_1170

; template <class Epi>
; __device__ __forceinline__ void gemm_phase(LAS unsigned char* lds, int wave_s, const Gemm g, const StaticOrder S, const Epi E) {
;     ...
;         const bool has_next = S.next(ui + 1, nxt);
;         const char* nA = has_next ? (const char*)g.A + (size_t)nxt.pm * tstepA : cA; const char* nB = has_next ? (const char*)g.Bt + (size_t)nxt.pn * tstepB : cB;
;     ...
; #pragma unroll
;         for (int a = 0; a < 2; ++a)
; #pragma unroll
;             for (int b = 0; b < 2; ++b)
; #pragma unroll
;                 for (int m = 0; m < 4; ++m)
; #pragma unroll
;                     for (int n = 0; n < 2; ++n) acc[a][b][m][n] = (f32x4){0.f, 0.f, 0.f, 0.f};
.LBB0_1170:
	s_ashr_i32 s17, s16, 31
	s_lshl_b64 s[0:1], s[16:17], 17
	s_add_u32 s18, s20, s0
	s_addc_u32 s19, s21, s1
	s_and_b64 s[0:1], s[42:43], exec
	s_cselect_b32 s17, s19, s25
	s_cselect_b32 s56, s18, s24
	s_ashr_i32 s15, s14, 31
	s_lshl_b64 s[0:1], s[14:15], 17
	v_readlane_b32 s6, v255, 4
	v_readlane_b32 s7, v255, 5
	s_add_u32 s20, s6, s0
	s_addc_u32 s21, s7, s1
	s_and_b64 s[0:1], s[42:43], exec
	v_mov_b32_e32 v2, 0
	s_cselect_b32 s15, s21, s23
	s_cselect_b32 s10, s20, s22
	s_mov_b32 s11, 0
	s_mov_b64 s[26:27], -1
	s_mov_b64 s[28:29], 0
	v_mov_b32_e32 v3, v2
	v_mov_b32_e32 v4, v2
	v_mov_b32_e32 v5, v2
	v_mov_b32_e32 v6, v2
	v_mov_b32_e32 v7, v2
	v_mov_b32_e32 v8, v2
	v_mov_b32_e32 v9, v2
	v_mov_b32_e32 v10, v2
	v_mov_b32_e32 v11, v2
	v_mov_b32_e32 v12, v2
	v_mov_b32_e32 v13, v2
	v_mov_b32_e32 v14, v2
	v_mov_b32_e32 v15, v2
	v_mov_b32_e32 v16, v2
	v_mov_b32_e32 v17, v2

;     __device__ __forceinline__ bool next(int i, Unit& u) const {
;         const long L = (long)i * G + c; if (L >= nwg) return false;
;         int wgid = (int)L; { const int q = nwg / NXCD, r = nwg % NXCD, xcd = wgid % NXCD, off = wgid / NXCD; wgid = (xcd < r ? xcd * (q + 1) : r * (q + 1) + (xcd - r) * q) + off; }
;         const int nig = WGM * nN, gid = wgid / nig, fm = gid * WGM, gsz = (nM - fm) < WGM ? (nM - fm) : WGM;
;         u.pm = fm + ((wgid % nig) % gsz); u.pn = (wgid % nig) / gsz; return true;
;     }
; template <class Epi>
; __device__ __forceinline__ void gemm_phase(LAS unsigned char* lds, int wave_s, const Gemm g, const StaticOrder S, const Epi E) {
;     ...
;         const bool has_next = S.next(ui + 1, nxt);
.LBB0_1328:
	v_mov_b32_e32 v246, 0
	v_mov_b32_e32 v247, 0
	v_mov_b32_e32 v248, 0
	v_mov_b32_e32 v249, 0
	s_add_i32 s26, s26, 1
	v_readlane_b32 s6, v252, 18
	s_mul_i32 s6, s26, s6
	s_mul_hi_u32 s7, s26, s30
	s_add_i32 s7, s7, s6
	s_mul_i32 s6, s26, s30
	v_readlane_b32 s10, v252, 36
	v_readlane_b32 s11, v252, 37
	s_add_u32 s16, s6, s10
	s_addc_u32 s17, s7, s11
	s_waitcnt lgkmcnt(0)
	v_mov_b64_e32 v[2:3], 0x400
	v_cmp_gt_i64_e32 vcc, s[16:17], v[204:205]
	v_cmp_lt_i64_e64 s[42:43], s[16:17], v[2:3]
	s_cbranch_vccnz .Lzs_9
	s_ashr_i32 s6, s16, 31
	s_lshr_b32 s6, s6, 29
	s_add_i32 s6, s16, s6
	s_and_b32 s7, s6, -8
	s_sub_i32 s7, s16, s7
	s_cmp_gt_i32 s7, -1
	s_mov_b64 s[16:17], -1
	s_cbranch_scc0 .LBB0_1331
	s_lshl_b32 s10, s7, 7
	s_mov_b64 s[16:17], 0

;     __device__ __forceinline__ bool next(int i, Unit& u) const {
;         const long L = (long)i * G + c; if (L >= nwg) return false;
;         int wgid = (int)L; { const int q = nwg / NXCD, r = nwg % NXCD, xcd = wgid % NXCD, off = wgid / NXCD; wgid = (xcd < r ? xcd * (q + 1) : r * (q + 1) + (xcd - r) * q) + off; }
;         const int nig = WGM * nN, gid = wgid / nig, fm = gid * WGM, gsz = (nM - fm) < WGM ? (nM - fm) : WGM;
;         u.pm = fm + ((wgid % nig) % gsz); u.pn = (wgid % nig) / gsz; return true;
;     }
.LBB0_1333:
	s_ashr_i32 s6, s6, 3
	s_add_i32 s6, s10, s6
	v_mfma_f32_32x32x16_bf16 v[18:33], v[246:249], v[246:249], 0
	s_ashr_i32 s7, s6, 31
	s_lshr_b32 s7, s7, 27
	s_add_i32 s7, s6, s7
	s_ashr_i32 s10, s7, 5
	s_lshl_b32 s10, s10, 3
	v_mfma_f32_32x32x16_bf16 v[34:49], v[246:249], v[246:249], 0
	s_sub_i32 s11, 0x100, s10
	s_min_i32 s11, s11, 8
	s_abs_i32 s16, s11
	v_cvt_f32_u32_e32 v2, s16
	s_sub_i32 s28, 0, s16
	v_mfma_f32_32x32x16_bf16 v[50:65], v[246:249], v[246:249], 0
	s_andn2_b32 s7, s7, 31
	s_sub_i32 s6, s6, s7
	v_rcp_iflag_f32_e32 v2, v2
	s_abs_i32 s7, s6
	s_xor_b32 s17, s6, s11
	v_mfma_f32_32x32x16_bf16 v[66:81], v[246:249], v[246:249], 0
	s_ashr_i32 s17, s17, 31
	v_mul_f32_e32 v2, 0x4f7ffffe, v2
	v_cvt_u32_f32_e32 v2, v2
	s_nop 0
	v_readfirstlane_b32 s29, v2
	v_mfma_f32_32x32x16_bf16 v[82:97], v[246:249], v[246:249], 0
	s_mul_i32 s28, s28, s29
	s_mul_hi_u32 s28, s29, s28
	s_add_i32 s29, s29, s28
	s_mul_hi_u32 s28, s7, s29
	s_mul_i32 s29, s28, s16
	v_mfma_f32_32x32x16_bf16 v[98:113], v[246:249], v[246:249], 0
	s_sub_i32 s7, s7, s29
	s_add_i32 s30, s28, 1
	s_sub_i32 s29, s7, s16
	s_cmp_ge_u32 s7, s16
	s_cselect_b32 s28, s30, s28
	v_mfma_f32_32x32x16_bf16 v[114:129], v[246:249], v[246:249], 0
	s_cselect_b32 s7, s29, s7
	s_add_i32 s29, s28, 1
	s_cmp_ge_u32 s7, s16
	s_cselect_b32 s7, s29, s28
	s_xor_b32 s7, s7, s17
	s_sub_i32 s56, s7, s17
	s_mul_i32 s7, s56, s11
	s_sub_i32 s6, s6, s7
	s_add_i32 s48, s10, s6
	s_branch .LBB0_1334

; template <class Epi>
; __device__ __forceinline__ void gemm_phase(LAS unsigned char* lds, int wave_s, const Gemm g, const StaticOrder S, const Epi E) {
;     ...
;         const bool has_next = S.next(ui + 1, nxt);
;         const char* nA = has_next ? (const char*)g.A + (size_t)nxt.pm * tstepA : cA; const char* nB = has_next ? (const char*)g.Bt + (size_t)nxt.pn * tstepB : cB;
;     ...
; #pragma unroll
;         for (int a = 0; a < 2; ++a)
; #pragma unroll
;             for (int b = 0; b < 2; ++b)
; #pragma unroll
;                 for (int m = 0; m < 4; ++m)
; #pragma unroll
;                     for (int n = 0; n < 2; ++n) acc[a][b][m][n] = (f32x4){0.f, 0.f, 0.f, 0.f};
.LBB0_1334:
	s_ashr_i32 s49, s48, 31
	s_lshl_b64 s[6:7], s[48:49], 19
	v_readlane_b32 s10, v253, 35
	v_readlane_b32 s11, v253, 36
	s_add_u32 s50, s10, s6
	s_addc_u32 s51, s11, s7
	s_and_b64 s[6:7], s[42:43], exec
	s_cselect_b32 s28, s51, s13
	s_cselect_b32 s29, s50, s12
	s_ashr_i32 s57, s56, 31
	s_lshl_b64 s[6:7], s[56:57], 19
	v_readlane_b32 s10, v253, 31
	v_readlane_b32 s11, v253, 32
	s_add_u32 s52, s10, s6
	s_addc_u32 s53, s11, s7
	s_and_b64 s[6:7], s[42:43], exec
	s_cselect_b32 s10, s53, s15
	s_cselect_b32 s11, s52, s14
	s_add_u32 s12, s12, 0x40080
	s_addc_u32 s13, s13, 0
	s_add_u32 s30, s14, 0x100
	v_mov_b32_e32 v2, 0
	s_addc_u32 s31, s15, 0
	s_mov_b32 s34, -2
	v_mov_b32_e32 v3, v2
	v_mov_b32_e32 v4, v2
	v_mov_b32_e32 v5, v2
	v_mov_b32_e32 v6, v2
	v_mov_b32_e32 v7, v2
	v_mov_b32_e32 v8, v2
	v_mov_b32_e32 v9, v2
	v_mov_b32_e32 v10, v2
	v_mov_b32_e32 v11, v2
	v_mov_b32_e32 v12, v2
	v_mov_b32_e32 v13, v2
	v_mov_b32_e32 v14, v2
	v_mov_b32_e32 v15, v2
	v_mov_b32_e32 v16, v2
	v_mov_b32_e32 v17, v2
